# K=2816 sample-row task after the down GEMM: all 33 operand loads issued up front into distinct registers, MFMAs behind counted waits in the baseline order
# baseline (speedup 1.0000x reference)
.LBB0_670:
	v_mov_b32_e32 v84, v201
	s_movk_i32 s2, 0x160
	v_ashrrev_i32_e32 v85, 6, v84
	v_and_b32_e32 v0, 15, v84
	v_mov_b64_e32 v[2:3], s[6:7]
	v_lshrrev_b32_e32 v4, 1, v84
	v_mul_lo_u32 v5, v85, s2
	v_mul_u32_u24_e32 v6, 0xb00, v0
	v_add_u32_e32 v7, s8, v0
	v_and_or_b32 v4, v4, 24, v5
	v_lshlrev_b32_e32 v0, 1, v6
	v_mad_i64_i32 v[2:3], s[10:11], v7, s14, v[2:3]
	v_lshl_add_u64 v[6:7], s[4:5], 0, v[0:1]
	v_ashrrev_i32_e32 v5, 31, v4
	v_add_u32_e32 v8, 32, v4
	v_add_u32_e32 v10, 64, v4
	v_add_u32_e32 v12, 0x60, v4
	v_add_u32_e32 v14, 0x80, v4
	s_mov_b64 s[10:11], 0x16000
	v_add_u32_e32 v16, 0xa0, v4
	v_add_u32_e32 v18, 0xc0, v4
	v_add_u32_e32 v20, 0xe0, v4
	v_add_u32_e32 v22, 0x100, v4
	v_add_u32_e32 v24, 0x120, v4
	v_add_u32_e32 v26, 0x140, v4
	v_lshl_add_u64 v[28:29], v[6:7], 0, s[10:11]
	v_lshlrev_b64 v[4:5], 1, v[4:5]
	v_ashrrev_i32_e32 v9, 31, v8
	v_ashrrev_i32_e32 v11, 31, v10
	v_ashrrev_i32_e32 v13, 31, v12
	v_ashrrev_i32_e32 v15, 31, v14
	v_ashrrev_i32_e32 v17, 31, v16
	v_ashrrev_i32_e32 v19, 31, v18
	v_ashrrev_i32_e32 v21, 31, v20
	v_ashrrev_i32_e32 v23, 31, v22
	v_ashrrev_i32_e32 v25, 31, v24
	v_ashrrev_i32_e32 v27, 31, v26
	v_lshl_add_u64 v[30:31], v[28:29], 0, v[4:5]
	v_lshl_add_u64 v[72:73], v[2:3], 0, v[4:5]
	v_lshl_add_u64 v[32:33], v[8:9], 1, v[28:29]
	v_lshl_add_u64 v[34:35], v[10:11], 1, v[28:29]
	v_lshl_add_u64 v[46:47], v[12:13], 1, v[28:29]
	v_lshl_add_u64 v[58:59], v[14:15], 1, v[28:29]
	s_barrier
	v_lshl_add_u64 v[70:71], v[6:7], 0, v[4:5]
	v_lshl_add_u64 v[66:67], v[16:17], 1, v[28:29]
	v_lshl_add_u64 v[74:75], v[18:19], 1, v[28:29]
	v_lshl_add_u64 v[76:77], v[20:21], 1, v[28:29]
	v_lshl_add_u64 v[78:79], v[22:23], 1, v[28:29]
	v_lshl_add_u64 v[80:81], v[24:25], 1, v[28:29]
	v_lshl_add_u64 v[82:83], v[26:27], 1, v[28:29]
	global_load_dwordx4 v[86:89], v[72:73], off
	global_load_dwordx4 v[90:93], v[70:71], off
	global_load_dwordx4 v[94:97], v[30:31], off
	global_load_dwordx4 v[98:101], v[72:73], off offset:64
	global_load_dwordx4 v[102:105], v[70:71], off offset:64
	global_load_dwordx4 v[106:109], v[32:33], off
	global_load_dwordx4 v[110:113], v[72:73], off offset:128
	global_load_dwordx4 v[114:117], v[70:71], off offset:128
	global_load_dwordx4 v[118:121], v[34:35], off
	global_load_dwordx4 v[122:125], v[72:73], off offset:192
	global_load_dwordx4 v[126:129], v[70:71], off offset:192
	global_load_dwordx4 v[130:133], v[46:47], off
	global_load_dwordx4 v[134:137], v[72:73], off offset:256
	global_load_dwordx4 v[138:141], v[70:71], off offset:256
	global_load_dwordx4 v[142:145], v[58:59], off
	global_load_dwordx4 v[146:149], v[72:73], off offset:320
	global_load_dwordx4 v[150:153], v[70:71], off offset:320
	global_load_dwordx4 v[154:157], v[66:67], off
	global_load_dwordx4 v[158:161], v[72:73], off offset:384
	global_load_dwordx4 v[162:165], v[70:71], off offset:384
	global_load_dwordx4 v[166:169], v[74:75], off
	global_load_dwordx4 v[170:173], v[72:73], off offset:448
	global_load_dwordx4 v[174:177], v[70:71], off offset:448
	global_load_dwordx4 v[178:181], v[76:77], off
	global_load_dwordx4 v[182:185], v[72:73], off offset:512
	global_load_dwordx4 v[186:189], v[70:71], off offset:512
	global_load_dwordx4 v[190:193], v[78:79], off
	global_load_dwordx4 v[202:205], v[72:73], off offset:576
	global_load_dwordx4 v[206:209], v[70:71], off offset:576
	global_load_dwordx4 v[210:213], v[80:81], off
	global_load_dwordx4 v[214:217], v[72:73], off offset:640
	global_load_dwordx4 v[218:221], v[70:71], off offset:640
	global_load_dwordx4 v[222:225], v[82:83], off
	v_lshlrev_b32_e32 v0, 4, v84
	v_and_b32_e32 v0, 0x3f0, v0
	s_and_b32 s10, s8, 0xffffffe0
	s_ashr_i32 s11, s10, 31
	s_lshr_b32 s2, s8, 1
	s_and_b32 s2, s2, 8
	s_add_i32 s9, s9, s12
	s_add_i32 s8, s8, s13
	s_cmp_gt_i32 s9, 63
	v_ashrrev_i32_e32 v24, 8, v84
	v_bfe_u32 v22, v84, 2, 4
	v_lshl_or_b32 v22, v24, 4, v22
	v_lshlrev_b32_e32 v23, 11, v85
	v_add_u32_e32 v22, 0x8000, v22
	v_add3_u32 v27, 0, v23, v0
	v_ashrrev_i32_e32 v23, 31, v22
	v_lshrrev_b32_e32 v25, 2, v84
	v_and_b32_e32 v0, 48, v25
	v_and_b32_e32 v26, 3, v84
	v_lshlrev_b64 v[10:11], 11, v[22:23]
	v_lshl_add_u64 v[10:11], s[16:17], 0, v[10:11]
	v_lshl_add_u64 v[10:11], s[10:11], 1, v[10:11]
	v_lshl_add_u64 v[10:11], v[10:11], 0, v[0:1]
	v_lshlrev_b32_e32 v0, 1, v26
	v_lshl_add_u64 v[10:11], v[10:11], 0, s[2:3]
	v_lshl_add_u64 v[10:11], v[10:11], 0, v[0:1]
	s_waitcnt vmcnt(31)
	v_mfma_f32_16x16x32_bf16 v[6:9], v[86:89], v[90:93], 0
	s_waitcnt vmcnt(30)
	v_mfma_f32_16x16x32_bf16 v[2:5], v[86:89], v[94:97], 0
	s_waitcnt vmcnt(28)
	v_mfma_f32_16x16x32_bf16 v[6:9], v[98:101], v[102:105], v[6:9]
	s_waitcnt vmcnt(27)
	v_mfma_f32_16x16x32_bf16 v[2:5], v[98:101], v[106:109], v[2:5]
	s_waitcnt vmcnt(25)
	v_mfma_f32_16x16x32_bf16 v[6:9], v[110:113], v[114:117], v[6:9]
	s_waitcnt vmcnt(24)
	v_mfma_f32_16x16x32_bf16 v[2:5], v[110:113], v[118:121], v[2:5]
	s_waitcnt vmcnt(22)
	v_mfma_f32_16x16x32_bf16 v[6:9], v[122:125], v[126:129], v[6:9]
	s_waitcnt vmcnt(21)
	v_mfma_f32_16x16x32_bf16 v[2:5], v[122:125], v[130:133], v[2:5]
	s_waitcnt vmcnt(19)
	v_mfma_f32_16x16x32_bf16 v[6:9], v[134:137], v[138:141], v[6:9]
	s_waitcnt vmcnt(18)
	v_mfma_f32_16x16x32_bf16 v[2:5], v[134:137], v[142:145], v[2:5]
	s_waitcnt vmcnt(16)
	v_mfma_f32_16x16x32_bf16 v[6:9], v[146:149], v[150:153], v[6:9]
	s_waitcnt vmcnt(15)
	v_mfma_f32_16x16x32_bf16 v[2:5], v[146:149], v[154:157], v[2:5]
	s_waitcnt vmcnt(13)
	v_mfma_f32_16x16x32_bf16 v[6:9], v[158:161], v[162:165], v[6:9]
	s_waitcnt vmcnt(12)
	v_mfma_f32_16x16x32_bf16 v[2:5], v[158:161], v[166:169], v[2:5]
	s_waitcnt vmcnt(10)
	v_mfma_f32_16x16x32_bf16 v[6:9], v[170:173], v[174:177], v[6:9]
	s_waitcnt vmcnt(9)
	v_mfma_f32_16x16x32_bf16 v[2:5], v[170:173], v[178:181], v[2:5]
	s_waitcnt vmcnt(7)
	v_mfma_f32_16x16x32_bf16 v[6:9], v[182:185], v[186:189], v[6:9]
	s_waitcnt vmcnt(6)
	v_mfma_f32_16x16x32_bf16 v[2:5], v[182:185], v[190:193], v[2:5]
	s_waitcnt vmcnt(4)
	v_mfma_f32_16x16x32_bf16 v[6:9], v[202:205], v[206:209], v[6:9]
	s_waitcnt vmcnt(3)
	v_mfma_f32_16x16x32_bf16 v[2:5], v[202:205], v[210:213], v[2:5]
	s_waitcnt vmcnt(1)
	v_mfma_f32_16x16x32_bf16 v[6:9], v[214:217], v[218:221], v[6:9]
	s_waitcnt vmcnt(0)
	v_mfma_f32_16x16x32_bf16 v[2:5], v[214:217], v[222:225], v[2:5]
	s_nop 4
	ds_write_b128 v27, v[6:9]
	s_nop 1
	ds_write_b128 v27, v[2:5] offset:1024
	s_waitcnt lgkmcnt(0)
	s_barrier
	global_load_ushort v0, v[10:11], off
	v_lshlrev_b32_e32 v2, 2, v84
	v_lshl_add_u32 v3, v26, 2, 0
	v_lshlrev_b32_e32 v4, 10, v24
	v_and_b32_e32 v2, 0x3f0, v2
	v_add3_u32 v8, v3, v4, v2
	ds_read2st64_b32 v[2:3], v8 offset1:8
	ds_read2st64_b32 v[4:5], v8 offset0:16 offset1:24
	ds_read2st64_b32 v[6:7], v8 offset0:32 offset1:40
	ds_read2st64_b32 v[8:9], v8 offset0:48 offset1:56
	s_waitcnt lgkmcnt(3)
	v_add_f32_e32 v2, 0, v2
	v_add_f32_e32 v2, v2, v3
	s_waitcnt lgkmcnt(2)
	v_add_f32_e32 v2, v2, v4
	v_add_f32_e32 v2, v2, v5
	s_waitcnt lgkmcnt(1)
	v_add_f32_e32 v2, v2, v6
	v_add_f32_e32 v2, v2, v7
	s_waitcnt lgkmcnt(0)
	v_add_f32_e32 v2, v2, v8
	v_add_f32_e32 v2, v2, v9
	s_waitcnt vmcnt(0)
	v_lshlrev_b32_e32 v0, 16, v0
	v_fmac_f32_e32 v0, 0.5, v2
	v_cvt_pk_bf16_f32 v0, v0, v1
	global_store_short v[10:11], v0, off
	s_cbranch_scc0 .LBB0_670

.Lbgc_done2:
	s_mov_b64 s[100:101], 0
	s_branch .LBB0_685
	s_nop 0
	s_nop 0
	s_nop 0
	s_nop 0
	s_nop 0
	s_nop 0
	s_nop 0
	s_nop 0
	s_nop 0
	s_nop 0
	s_nop 0
	s_nop 0
	s_nop 0
	s_nop 0
